# SSD S3 decay-matrix build: 64 exec-guarded serialized LDS round trips per head replaced by batched double-buffered ds_read_b128 + full-exec math + v_cndmask masks (same ops, same order)
# speedup vs baseline: 1.0052x; 1.0052x over previous
; #define LAS __attribute__((address_space(3)))
; #define LDS_WAIT() asm volatile("s_waitcnt lgkmcnt(0)" ::: "memory")
; __device__ __forceinline__ f32x4 mfma16(bf16x8 bfrag, bf16x8 afrag, f32x4 acc) { return __builtin_amdgcn_mfma_f32_16x16x32_bf16(bfrag, afrag, acc, 0, 0, 0); }
; __device__ __forceinline__ void ssd_s3_unit(LAS unsigned char* lds, int unit, const bf16_t* P0, const float* cw, const float* cb, const float* dt_bias, const float* a_log, const float* dskip, const float* norm_w,
;                                             const bf16_t* STATES, bf16_t* OMIX) {
;     ...
;         LDS_WAIT();
; #pragma unroll
;         for (int ks = 0; ks < 4; ++ks)
; #pragma unroll
;             for (int pt = 0; pt < 4; ++pt) cB[ks][pt] = *(const bf16x8*)(carb + (pt * 16 + fr) * 128 + ks * 32 + fq * 8);
;         f32x4 yd[4], yf[4], yb[4];
; #pragma unroll
;         for (int pt = 0; pt < 4; ++pt) { yd[pt] = (f32x4){0.f, 0.f, 0.f, 0.f}; yf[pt] = yd[pt]; yb[pt] = yd[pt]; }
;         bf16x8 acs[4];
; #pragma unroll
;         for (int ks = 0; ks < 4; ++ks) {
;             const bf16x8 am = *(const LAS bf16x8*)(Mw + fr * SLD + ks * 32 + fq * 8); acs[ks] = ldsfrag(CS, SLD, 16 * w, ks * 32, fr, fq);
; #pragma unroll
;             for (int pt = 0; pt < 4; ++pt) {
;                 yd[pt] = mfma16(ldsfrag(XT, SLD, j * 64 + pt * 16, ks * 32, fr, fq), am, yd[pt]);
;                 yf[pt] = mfma16(cF[ks][pt], acs[ks], yf[pt]); }
;         }
; #pragma unroll
;         for (int ks = 0; ks < 4; ++ks)
; #pragma unroll
;             for (int pt = 0; pt < 4; ++pt) yb[pt] = mfma16(cB[ks][pt], acs[ks], yb[pt]);
.LBB0_843:
	v_add_u32_e32 v201, 0, v179
	s_waitcnt lgkmcnt(0)
	v_add_u32_e32 v96, 0x11000, v201
	ds_read_b128 v[96:99], v96
	v_add_u32_e32 v121, v154, v106
	ds_read_b128 v[186:189], v121 offset:34816
	v_add_u32_e32 v100, 0x12100, v201
	v_add_u32_e32 v119, 0x13200, v201
	ds_read_b128 v[190:193], v100
	ds_read_b128 v[194:197], v121 offset:34880
	s_waitcnt lgkmcnt(2)
	v_mfma_f32_16x16x32_bf16 v[202:205], v[96:99], v[186:189], 0
	ds_read_b128 v[100:103], v178
	ds_read_b128 v[96:99], v178 offset:64
	ds_read_b128 v[206:209], v119
	v_add_u32_e32 v119, 0x14300, v201
	ds_read_b128 v[210:213], v119
	v_add_u32_e32 v119, 0x11040, v201
	s_waitcnt lgkmcnt(5)
	v_mfma_f32_16x16x32_bf16 v[190:193], v[190:193], v[186:189], 0
	s_lshl_b64 s[60:61], s[56:57], 1
	s_bitset1_b32 s60, 17
	v_lshl_add_u64 v[198:199], v[110:111], 0, s[60:61]
	s_waitcnt lgkmcnt(1)
	v_mfma_f32_16x16x32_bf16 v[206:209], v[206:209], v[186:189], 0
	v_lshl_add_u64 v[234:235], v[198:199], 0, v[108:109]
	v_mov_b32_e32 v123, v109
	v_lshl_add_u64 v[238:239], v[198:199], 0, s[54:55]
	s_waitcnt lgkmcnt(0)
	v_mfma_f32_16x16x32_bf16 v[186:189], v[210:213], v[186:189], 0
	ds_read_b128 v[210:213], v119
	v_add_u32_e32 v119, 0x12140, v201
	ds_read_b128 v[214:217], v119
	s_waitcnt vmcnt(18)
	v_mfma_f32_16x16x32_bf16 v[80:83], v[80:83], v[100:103], 0
	v_add_u32_e32 v119, 0x13240, v201
	s_mov_b64 s[60:61], 0xc0
	v_add_u32_e32 v182, 0x400, v182
	v_mfma_f32_16x16x32_bf16 v[84:87], v[84:87], v[100:103], 0
	v_add_u32_e32 v181, 0x400, v181
	v_add_u32_e32 v179, 0x4400, v179
	v_lshl_add_u64 v[132:133], v[132:133], 0, s[54:55]
	s_waitcnt vmcnt(13)
	v_mfma_f32_16x16x32_bf16 v[72:75], v[72:75], v[96:99], v[80:83]
	s_nop 2
	v_add_u32_e32 v80, 0x14340, v201
	v_mfma_f32_16x16x32_bf16 v[76:79], v[76:79], v[96:99], v[84:87]
	ds_read_b128 v[80:83], v80
	s_waitcnt lgkmcnt(1)
	v_mfma_f32_16x16x32_bf16 v[84:87], v[214:217], v[194:197], v[190:193]
	s_nop 2
	ds_read_b128 v[190:193], v119
	s_waitcnt vmcnt(9)
	v_mfma_f32_16x16x32_bf16 v[92:95], v[92:95], v[100:103], 0
	v_mov_b32_e32 v119, v109
	v_mfma_f32_16x16x32_bf16 v[92:95], v[68:71], v[96:99], v[92:95]
	v_add_u32_e32 v68, 0x11080, v201
	v_mfma_f32_16x16x32_bf16 v[202:205], v[210:213], v[194:197], v[202:205]
	ds_read_b128 v[210:213], v68
	v_mfma_f32_16x16x32_bf16 v[88:91], v[88:91], v[100:103], 0
	s_waitcnt lgkmcnt(1)
	v_mfma_f32_16x16x32_bf16 v[190:193], v[190:193], v[194:197], v[206:209]
	s_nop 2
	global_load_dwordx4 v[206:209], v[234:235], off
	v_mfma_f32_16x16x32_bf16 v[80:83], v[80:83], v[194:197], v[186:189]
	s_nop 2
	ds_read_b128 v[186:189], v121 offset:34944
	ds_read_b128 v[68:71], v178 offset:128
	v_mfma_f32_16x16x32_bf16 v[88:91], v[64:67], v[96:99], v[88:91]
	v_add_u32_e32 v64, 0x12180, v201
	ds_read_b128 v[194:197], v64
	ds_read_b128 v[214:217], v121 offset:35008
	ds_read_b128 v[64:67], v178 offset:192
	s_waitcnt lgkmcnt(3)
	v_mfma_f32_16x16x32_bf16 v[60:63], v[60:63], v[68:71], v[76:79]
	v_mov_b32_e32 v121, v109
	s_nop 1
	v_add_u32_e32 v76, 0x13280, v201
	ds_read_b128 v[76:79], v76
	v_mfma_f32_16x16x32_bf16 v[202:205], v[210:213], v[186:189], v[202:205]
	v_lshl_add_u64 v[210:211], v[198:199], 0, v[118:119]
	v_lshl_add_u64 v[212:213], v[198:199], 0, v[120:121]
	v_mfma_f32_16x16x32_bf16 v[218:221], v[56:59], v[68:71], v[72:75]
	v_add_u32_e32 v56, 0x14380, v201
	s_waitcnt lgkmcnt(3)
	v_mfma_f32_16x16x32_bf16 v[84:87], v[194:197], v[186:189], v[84:87]
	global_load_dwordx4 v[194:197], v[210:211], off
	s_nop 0
	global_load_dwordx4 v[210:213], v[212:213], off
	ds_read_b128 v[56:59], v56
	v_lshl_add_u64 v[72:73], v[198:199], 0, v[122:123]
	s_waitcnt vmcnt(10)
	v_mfma_f32_16x16x32_bf16 v[92:95], v[52:55], v[68:71], v[92:95]
	v_add_u32_e32 v52, 0x110c0, v201
	ds_read_b128 v[52:55], v52
	global_load_dwordx4 v[222:225], v[234:235], off offset:64
	s_waitcnt vmcnt(9)
	v_mfma_f32_16x16x32_bf16 v[88:91], v[48:51], v[68:71], v[88:91]
	v_add_u32_e32 v48, 0x121c0, v201
	ds_read_b128 v[48:51], v48
	global_load_dwordx4 v[230:233], v[234:235], off offset:128
	s_waitcnt lgkmcnt(3)
	v_mfma_f32_16x16x32_bf16 v[76:79], v[76:79], v[186:189], v[190:193]
	s_nop 2
	global_load_dwordx4 v[190:193], v[72:73], off
	v_lshl_add_u64 v[72:73], v[198:199], 0, 64
	v_lshl_add_u64 v[74:75], v[72:73], 0, v[118:119]
	s_waitcnt lgkmcnt(2)
	v_mfma_f32_16x16x32_bf16 v[80:83], v[56:59], v[186:189], v[80:83]
	global_load_dwordx4 v[186:189], v[74:75], off
	v_lshl_add_u64 v[56:57], v[72:73], 0, v[120:121]
	v_lshl_add_u64 v[72:73], v[72:73], 0, v[122:123]
	global_load_dwordx4 v[226:229], v[56:57], off
	s_waitcnt lgkmcnt(1)
	v_mfma_f32_16x16x32_bf16 v[56:59], v[52:55], v[214:217], v[202:205]
	s_nop 2
	global_load_dwordx4 v[202:205], v[72:73], off
	v_mfma_f32_16x16x32_bf16 v[72:75], v[44:47], v[64:67], v[60:63]
	v_lshl_add_u64 v[44:45], v[238:239], 0, v[118:119]
	s_waitcnt lgkmcnt(0)
	v_mfma_f32_16x16x32_bf16 v[48:51], v[48:51], v[214:217], v[84:87]
	global_load_dwordx4 v[60:63], v[44:45], off
	s_nop 1
	global_load_dwordx4 v[84:87], v[234:235], off offset:192
	v_lshl_add_u64 v[234:235], v[238:239], 0, v[120:121]
	v_mfma_f32_16x16x32_bf16 v[52:55], v[40:43], v[64:67], v[218:221]
	v_add_u32_e32 v40, 0x143c0, v201
	s_nop 1
	global_load_dwordx4 v[218:221], v[234:235], off
	v_add_u32_e32 v44, 0x132c0, v201
	ds_read_b128 v[44:47], v44
	ds_read_b128 v[234:237], v40
	s_waitcnt lgkmcnt(1)
	v_mfma_f32_16x16x32_bf16 v[40:43], v[44:47], v[214:217], v[76:79]
	v_lshl_add_u64 v[44:45], v[128:129], 0, s[58:59]
	s_nop 1
	global_load_dword v76, v[44:45], off
	v_lshl_add_u64 v[78:79], v[238:239], 0, v[122:123]
	v_mfma_f32_16x16x32_bf16 v[44:47], v[36:39], v[64:67], v[92:95]
	v_mul_f32_e32 v77, 0x3fb8aa3b, v185
	s_add_u32 s58, s58, 4
	s_addc_u32 s59, s59, 0
	global_load_dwordx4 v[92:95], v[78:79], off
	v_lshl_add_u64 v[78:79], v[198:199], 0, s[60:61]
	v_lshl_add_u64 v[198:199], v[78:79], 0, v[118:119]
	s_waitcnt lgkmcnt(0)
; __device__ __forceinline__ unsigned pk2(float lo, float hi) { const f32x2 v = {lo, hi}; return __builtin_bit_cast(unsigned, __builtin_convertvector(v, bf16x2_t)); }
; __device__ __forceinline__ float siluf_(float x) { return x * frcp(1.0f + __expf(-x)); }
; __device__ __forceinline__ f32x4 mfma16(bf16x8 bfrag, bf16x8 afrag, f32x4 acc) { return __builtin_amdgcn_mfma_f32_16x16x32_bf16(bfrag, afrag, acc, 0, 0, 0); }
; __device__ __forceinline__ void ssd_s3_unit(LAS unsigned char* lds, int unit, const bf16_t* P0, const float* cw, const float* cb, const float* dt_bias, const float* a_log, const float* dskip, const float* norm_w,
;                                             const bf16_t* STATES, bf16_t* OMIX) {
;     ...
; #pragma unroll
;         for (int ks = 0; ks < 4; ++ks)
; #pragma unroll
;             for (int pt = 0; pt < 4; ++pt) yb[pt] = mfma16(cB[ks][pt], acs[ks], yb[pt]);
;         const float ef = __expf(cfl), eb = __expf(cbl), dsk = dskip[g * 4 + j];
; #pragma unroll
;         for (int pt = 0; pt < 4; ++pt) { const f32x4 yv = yd[pt] + yf[pt] * ef + yb[pt] * eb;
;             const int col = j * 64 + pt * 16 + fq * 4; const u32x2 zz = zz4[pt];
;             const float z4[4] = {bflo(zz.x), bfhi(zz.x), bflo(zz.y), bfhi(zz.y)}; float v4[4];
; #pragma unroll
;             for (int i = 0; i < 4; ++i) { const float xs = bf2f(XT[(col + i) * SLD + l]); float v = yv[i] + dsk * xs; const float z = z4[i]; v = v * siluf_(z);
;                 v4[i] = v; ss += v * v; }
;             u32x2 o; o.x = pk2(v4[0], v4[1]); o.y = pk2(v4[2], v4[3]); *(u32x2*)(OMIX + row * D + 512 + g * 256 + col) = o; }
	v_mfma_f32_16x16x32_bf16 v[36:39], v[234:237], v[214:217], v[80:83]
	global_load_dwordx4 v[214:217], v[198:199], off
	s_waitcnt vmcnt(18)
	v_lshlrev_b32_e32 v198, 16, v142
	v_and_b32_e32 v199, 0xffff0000, v142
	v_lshl_add_u64 v[80:81], v[78:79], 0, v[120:121]
	v_lshl_add_u64 v[78:79], v[78:79], 0, v[122:123]
	v_mfma_f32_16x16x32_bf16 v[32:35], v[32:35], v[64:67], v[88:91]
	global_load_dwordx4 v[234:237], v[78:79], off
	v_exp_f32_e32 v78, v77
	v_mul_f32_e32 v77, 0x3fb8aa3b, v184
	global_load_dwordx4 v[88:91], v[80:81], off
	v_mul_f32_e32 v81, 0xbfb8aa3b, v198
	s_waitcnt vmcnt(16)
	v_mfma_f32_16x16x32_bf16 v[206:209], v[206:209], v[100:103], 0
	v_exp_f32_e32 v81, v81
	v_exp_f32_e32 v80, v77
	v_add_u32_e32 v77, 0, v180
	s_waitcnt vmcnt(15)
	v_mfma_f32_16x16x32_bf16 v[194:197], v[194:197], v[100:103], 0
	v_add_f32_e32 v81, 1.0, v81
	v_add_u32_e32 v79, 0x11000, v77
	v_add_u32_e32 v82, 0x11110, v77
	s_waitcnt vmcnt(14)
	v_mfma_f32_16x16x32_bf16 v[210:213], v[210:213], v[100:103], 0
	v_add_u32_e32 v119, 0x12100, v77
	v_add_u32_e32 v121, 0x12210, v77
	v_add_u32_e32 v123, 0x12320, v77
	s_waitcnt vmcnt(11)
	v_mfma_f32_16x16x32_bf16 v[100:103], v[190:193], v[100:103], 0
	v_add_u32_e32 v142, 0x12430, v77
	v_add_u32_e32 v83, 0x11330, v77
	v_readlane_b32 s60, v253, 0
	v_mfma_f32_16x16x32_bf16 v[190:193], v[222:225], v[96:99], v[206:209]
	v_readlane_b32 s61, v253, 1
	s_add_u32 s56, s56, 0x2000
	s_addc_u32 s57, s57, 0
	v_rcp_f32_e32 v206, v81
	v_add_u32_e32 v81, 0x11220, v77
	ds_read_u16 v79, v79
	ds_read_u16 v82, v82
	ds_read_u16 v81, v81
	ds_read_u16 v201, v83
	ds_read_u16 v119, v119
	ds_read_u16 v121, v121
	ds_read_u16 v123, v123
	ds_read_u16 v142, v142
	s_waitcnt vmcnt(10)
	v_mfma_f32_16x16x32_bf16 v[184:187], v[186:189], v[96:99], v[194:197]
	s_waitcnt lgkmcnt(6)
	v_lshlrev_b32_e32 v189, 16, v82
	v_mul_f32_e32 v82, 0xbfb8aa3b, v199
	v_exp_f32_e32 v82, v82
	s_waitcnt vmcnt(9)
	v_mfma_f32_16x16x32_bf16 v[194:197], v[226:229], v[96:99], v[210:213]
	v_fma_f32 v56, v78, v72, v56
	v_fma_f32 v57, v78, v73, v57
	v_lshlrev_b32_e32 v188, 16, v79
	v_add_f32_e32 v72, 1.0, v82
	s_waitcnt vmcnt(8)
	v_mfma_f32_16x16x32_bf16 v[96:99], v[202:205], v[96:99], v[100:103]
	v_rcp_f32_e32 v207, v72
	v_add_u32_e32 v180, 0x4400, v180
	s_cmp_eq_u32 s58, 16
	v_mfma_f32_16x16x32_bf16 v[100:103], v[230:233], v[68:71], v[190:193]
	v_mul_f32_e64 v72, v206, v198
	v_mul_f32_e64 v73, v207, v199
	s_waitcnt vmcnt(6)
	v_mfma_f32_16x16x32_bf16 v[82:85], v[84:87], v[64:67], v[100:103]
	v_mfma_f32_16x16x32_bf16 v[60:63], v[60:63], v[68:71], v[184:187]
	s_waitcnt vmcnt(5)
	v_mfma_f32_16x16x32_bf16 v[100:103], v[218:221], v[68:71], v[194:197]
	s_waitcnt lgkmcnt(5)
	s_nop 3
	v_pk_fma_f32 v[56:57], v[80:81], v[82:83], v[56:57] op_sel_hi:[0,1,1]
	s_waitcnt vmcnt(4)
	v_pk_fma_f32 v[56:57], v[76:77], v[188:189], v[56:57] op_sel_hi:[0,1,1]
	v_pk_mul_f32 v[56:57], v[72:73], v[56:57]
	s_waitcnt vmcnt(3)
	v_mfma_f32_16x16x32_bf16 v[68:71], v[92:95], v[68:71], v[96:99]
	v_mul_f32_e64 v72, v56, v56
	v_mul_f32_e64 v73, v57, v57
	v_add_f32_e32 v79, v183, v72
	v_lshlrev_b32_e32 v72, 16, v143
	v_mul_f32_e32 v82, 0xbfb8aa3b, v72
	v_exp_f32_e32 v82, v82
	s_waitcnt vmcnt(2)
	v_mfma_f32_16x16x32_bf16 v[92:95], v[214:217], v[64:67], v[60:63]
	v_add_f32_e32 v79, v79, v73
	v_and_b32_e32 v73, 0xffff0000, v143
	v_pk_fma_f32 v[58:59], v[78:79], v[74:75], v[58:59] op_sel_hi:[0,1,1]
	v_add_f32_e32 v60, 1.0, v82
	v_rcp_f32_e32 v82, v60
	v_mul_f32_e32 v60, 0xbfb8aa3b, v73
	v_exp_f32_e32 v83, v60
	s_waitcnt vmcnt(0)
	v_mfma_f32_16x16x32_bf16 v[86:89], v[88:91], v[64:67], v[100:103]
	v_fma_f32 v58, v80, v84, v58
	v_fma_f32 v59, v80, v85, v59
	v_pk_fma_f32 v[48:49], v[78:79], v[52:53], v[48:49] op_sel_hi:[0,1,1]
	v_pk_fma_f32 v[48:49], v[80:81], v[92:93], v[48:49] op_sel_hi:[0,1,1]
	v_mfma_f32_16x16x32_bf16 v[60:63], v[234:237], v[64:67], v[68:71]
	v_add_f32_e32 v66, 1.0, v83
	v_rcp_f32_e32 v83, v66
	s_waitcnt lgkmcnt(4)
	v_lshlrev_b32_e32 v65, 16, v201
	v_lshlrev_b32_e32 v64, 16, v81
	v_pk_fma_f32 v[58:59], v[76:77], v[64:65], v[58:59] op_sel_hi:[0,1,1]
	v_pk_mul_f32 v[64:65], v[82:83], v[72:73]
	s_waitcnt lgkmcnt(2)
	v_lshlrev_b32_e32 v67, 16, v121
	v_pk_mul_f32 v[58:59], v[64:65], v[58:59]
	v_pk_fma_f32 v[50:51], v[78:79], v[54:55], v[50:51] op_sel_hi:[0,1,1]
	v_pk_mul_f32 v[64:65], v[58:59], v[58:59]
	v_pk_fma_f32 v[50:51], v[80:81], v[94:95], v[50:51] op_sel_hi:[0,1,1]
	v_add_f32_e32 v64, v79, v64
	v_add_f32_e32 v68, v64, v65
	v_cvt_pk_bf16_f32 v65, v58, v59
	v_lshlrev_b32_e32 v58, 16, v140
	v_cvt_pk_bf16_f32 v64, v56, v57
	v_mul_f32_e32 v56, 0xbfb8aa3b, v58
	v_exp_f32_e32 v66, v56
	v_lshl_add_u64 v[56:57], s[60:61], 0, v[130:131]
	v_and_b32_e32 v59, 0xffff0000, v140
	global_store_dwordx2 v[56:57], v[64:65], off offset:-64
	v_mul_f32_e32 v65, 0xbfb8aa3b, v59
	v_exp_f32_e32 v65, v65
	v_add_f32_e32 v64, 1.0, v66
	v_rcp_f32_e32 v64, v64
	v_lshlrev_b32_e32 v66, 16, v119
	v_add_f32_e32 v65, 1.0, v65
	v_rcp_f32_e32 v65, v65
	v_pk_fma_f32 v[48:49], v[76:77], v[66:67], v[48:49] op_sel_hi:[0,1,1]
	v_pk_fma_f32 v[40:41], v[78:79], v[44:45], v[40:41] op_sel_hi:[0,1,1]
	v_pk_fma_f32 v[40:41], v[80:81], v[86:87], v[40:41] op_sel_hi:[0,1,1]
	v_pk_mul_f32 v[52:53], v[64:65], v[58:59]
	v_lshlrev_b32_e32 v58, 16, v141
	v_pk_mul_f32 v[48:49], v[52:53], v[48:49]
	v_mul_f32_e32 v59, 0xbfb8aa3b, v58
	v_pk_mul_f32 v[52:53], v[48:49], v[48:49]
	v_exp_f32_e32 v64, v59
	v_add_f32_e32 v52, v68, v52
	v_and_b32_e32 v59, 0xffff0000, v141
	v_add_f32_e32 v66, v52, v53
	v_mul_f32_e32 v53, 0xbfb8aa3b, v59
	v_exp_f32_e32 v53, v53
	v_add_f32_e32 v52, 1.0, v64
	v_rcp_f32_e32 v52, v52
	s_waitcnt lgkmcnt(0)
; __device__ __forceinline__ unsigned pk2(float lo, float hi) { const f32x2 v = {lo, hi}; return __builtin_bit_cast(unsigned, __builtin_convertvector(v, bf16x2_t)); }
; __device__ __forceinline__ float siluf_(float x) { return x * frcp(1.0f + __expf(-x)); }
; __device__ __forceinline__ void ssd_s3_unit(LAS unsigned char* lds, int unit, const bf16_t* P0, const float* cw, const float* cb, const float* dt_bias, const float* a_log, const float* dskip, const float* norm_w,
;                                             const bf16_t* STATES, bf16_t* OMIX) {
;     ...
;         const float ef = __expf(cfl), eb = __expf(cbl), dsk = dskip[g * 4 + j];
; #pragma unroll
;         for (int pt = 0; pt < 4; ++pt) { const f32x4 yv = yd[pt] + yf[pt] * ef + yb[pt] * eb;
;             const int col = j * 64 + pt * 16 + fq * 4; const u32x2 zz = zz4[pt];
;             const float z4[4] = {bflo(zz.x), bfhi(zz.x), bflo(zz.y), bfhi(zz.y)}; float v4[4];
; #pragma unroll
;             for (int i = 0; i < 4; ++i) { const float xs = bf2f(XT[(col + i) * SLD + l]); float v = yv[i] + dsk * xs; const float z = z4[i]; v = v * siluf_(z);
;                 v4[i] = v; ss += v * v; }
;             u32x2 o; o.x = pk2(v4[0], v4[1]); o.y = pk2(v4[2], v4[3]); *(u32x2*)(OMIX + row * D + 512 + g * 256 + col) = o; }
;         asm volatile("" ::: "memory");
;     }
	v_lshlrev_b32_e32 v65, 16, v142
	v_add_f32_e32 v53, 1.0, v53
	v_rcp_f32_e32 v53, v53
	v_lshlrev_b32_e32 v64, 16, v123
	v_pk_fma_f32 v[50:51], v[76:77], v[64:65], v[50:51] op_sel_hi:[0,1,1]
	v_cvt_pk_bf16_f32 v48, v48, v49
	v_pk_mul_f32 v[52:53], v[52:53], v[58:59]
	v_add_u32_e32 v58, 0x13530, v77
	v_pk_mul_f32 v[50:51], v[52:53], v[50:51]
	v_add_u32_e32 v59, 0x14300, v77
	v_cvt_pk_bf16_f32 v49, v50, v51
	global_store_dwordx2 v[56:57], v[48:49], off offset:-32
	v_lshlrev_b32_e32 v48, 16, v138
	v_pk_mul_f32 v[52:53], v[50:51], v[50:51]
	v_mul_f32_e32 v49, 0xbfb8aa3b, v48
	v_add_f32_e32 v52, v66, v52
	v_exp_f32_e32 v50, v49
	v_and_b32_e32 v49, 0xffff0000, v138
	v_add_f32_e32 v54, v52, v53
	v_mul_f32_e32 v53, 0xbfb8aa3b, v49
	v_exp_f32_e32 v55, v53
	v_add_u32_e32 v51, 0x13200, v77
	v_add_u32_e32 v52, 0x13310, v77
	v_add_u32_e32 v64, 0x14410, v77
	v_add_u32_e32 v65, 0x14520, v77
	v_add_u32_e32 v66, 0x14630, v77
	v_add_u32_e32 v53, 0x13420, v77
	ds_read_u16 v51, v51
	ds_read_u16 v52, v52
	ds_read_u16 v67, v53
	ds_read_u16 v58, v58
	ds_read_u16 v59, v59
	ds_read_u16 v64, v64
	ds_read_u16 v65, v65
	ds_read_u16 v66, v66
	v_add_f32_e32 v50, 1.0, v50
	s_waitcnt lgkmcnt(6)
	v_lshlrev_b32_e32 v53, 16, v52
	v_lshlrev_b32_e32 v52, 16, v51
	v_add_f32_e32 v51, 1.0, v55
	v_rcp_f32_e32 v50, v50
	v_rcp_f32_e32 v51, v51
	v_pk_fma_f32 v[40:41], v[76:77], v[52:53], v[40:41] op_sel_hi:[0,1,1]
	v_pk_fma_f32 v[42:43], v[78:79], v[46:47], v[42:43] op_sel_hi:[0,1,1]
	v_pk_fma_f32 v[42:43], v[80:81], v[88:89], v[42:43] op_sel_hi:[0,1,1]
	v_pk_mul_f32 v[44:45], v[50:51], v[48:49]
	v_lshlrev_b32_e32 v48, 16, v139
	v_pk_mul_f32 v[40:41], v[44:45], v[40:41]
	v_mul_f32_e32 v49, 0xbfb8aa3b, v48
	v_pk_mul_f32 v[44:45], v[40:41], v[40:41]
	v_exp_f32_e32 v50, v49
	v_add_f32_e32 v44, v54, v44
	v_and_b32_e32 v49, 0xffff0000, v139
	v_add_f32_e32 v52, v44, v45
	v_mul_f32_e32 v45, 0xbfb8aa3b, v49
	v_exp_f32_e32 v45, v45
	v_add_f32_e32 v44, 1.0, v50
	v_rcp_f32_e32 v44, v44
	s_waitcnt lgkmcnt(4)
	v_lshlrev_b32_e32 v51, 16, v58
	v_add_f32_e32 v45, 1.0, v45
	v_rcp_f32_e32 v45, v45
	v_lshlrev_b32_e32 v50, 16, v67
	v_pk_fma_f32 v[42:43], v[76:77], v[50:51], v[42:43] op_sel_hi:[0,1,1]
	v_cvt_pk_bf16_f32 v40, v40, v41
	v_pk_mul_f32 v[44:45], v[44:45], v[48:49]
	v_pk_fma_f32 v[32:33], v[78:79], v[32:33], v[36:37] op_sel_hi:[0,1,1]
	v_pk_mul_f32 v[42:43], v[44:45], v[42:43]
	v_pk_fma_f32 v[32:33], v[80:81], v[60:61], v[32:33] op_sel_hi:[0,1,1]
	v_pk_mul_f32 v[44:45], v[42:43], v[42:43]
	v_pk_fma_f32 v[34:35], v[78:79], v[34:35], v[38:39] op_sel_hi:[0,1,1]
	v_add_f32_e32 v44, v52, v44
	v_add_f32_e32 v46, v44, v45
	v_lshlrev_b32_e32 v44, 16, v136
	v_mul_f32_e32 v41, 0xbfb8aa3b, v44
	v_exp_f32_e32 v47, v41
	v_cvt_pk_bf16_f32 v41, v42, v43
	v_and_b32_e32 v45, 0xffff0000, v136
	global_store_dwordx2 v[56:57], v[40:41], off
	v_mul_f32_e32 v41, 0xbfb8aa3b, v45
	v_exp_f32_e32 v41, v41
	v_add_f32_e32 v40, 1.0, v47
	v_rcp_f32_e32 v40, v40
	s_waitcnt lgkmcnt(2)
	v_lshlrev_b32_e32 v43, 16, v64
	v_add_f32_e32 v41, 1.0, v41
	v_rcp_f32_e32 v41, v41
	v_lshlrev_b32_e32 v42, 16, v59
	v_pk_fma_f32 v[32:33], v[76:77], v[42:43], v[32:33] op_sel_hi:[0,1,1]
	s_waitcnt lgkmcnt(0)
	v_lshlrev_b32_e32 v43, 16, v66
	v_pk_mul_f32 v[36:37], v[40:41], v[44:45]
	v_lshlrev_b32_e32 v40, 16, v137
	v_pk_mul_f32 v[32:33], v[36:37], v[32:33]
	v_mul_f32_e32 v41, 0xbfb8aa3b, v40
	v_pk_mul_f32 v[36:37], v[32:33], v[32:33]
	v_exp_f32_e32 v42, v41
	v_add_f32_e32 v36, v46, v36
	v_and_b32_e32 v41, 0xffff0000, v137
	v_add_f32_e32 v44, v36, v37
	v_mul_f32_e32 v37, 0xbfb8aa3b, v41
	v_exp_f32_e32 v37, v37
	v_add_f32_e32 v36, 1.0, v42
	v_rcp_f32_e32 v36, v36
	v_lshlrev_b32_e32 v42, 16, v65
	v_add_f32_e32 v37, 1.0, v37
	v_rcp_f32_e32 v37, v37
	v_pk_fma_f32 v[34:35], v[80:81], v[62:63], v[34:35] op_sel_hi:[0,1,1]
	v_pk_fma_f32 v[34:35], v[76:77], v[42:43], v[34:35] op_sel_hi:[0,1,1]
	v_cvt_pk_bf16_f32 v32, v32, v33
	v_pk_mul_f32 v[36:37], v[36:37], v[40:41]
	s_mov_b64 s[60:61], 0x4000
	v_pk_mul_f32 v[34:35], v[36:37], v[34:35]
	v_lshl_add_u64 v[130:131], v[130:131], 0, s[54:55]
	v_cvt_pk_bf16_f32 v33, v34, v35
	global_store_dwordx2 v[56:57], v[32:33], off offset:32
	v_pk_mul_f32 v[36:37], v[34:35], v[34:35]
	v_lshl_add_u64 v[134:135], v[134:135], 0, s[60:61]
	v_add_f32_e32 v36, v44, v36
	v_add_f32_e32 v183, v36, v37
	s_cbranch_scc1 .LBB0_972
; #define LAS __attribute__((address_space(3)))
; __device__ __forceinline__ unsigned pk2(float lo, float hi) { const f32x2 v = {lo, hi}; return __builtin_bit_cast(unsigned, __builtin_convertvector(v, bf16x2_t)); }
; __device__ __forceinline__ void ssd_s3_unit(LAS unsigned char* lds, int unit, const bf16_t* P0, const float* cw, const float* cb, const float* dt_bias, const float* a_log, const float* dskip, const float* norm_w,
;                                             const bf16_t* STATES, bf16_t* OMIX) {
;     ...
;         bf16x8 cF[4][4], cB[4][4]; u32x2 zz4[4];
; #pragma unroll
;         for (int ks = 0; ks < 4; ++ks)
; #pragma unroll
;             for (int pt = 0; pt < 4; ++pt) cF[ks][pt] = *(const bf16x8*)(carf + (pt * 16 + fr) * 128 + ks * 32 + fq * 8);
; #pragma unroll
;         for (int pt = 0; pt < 4; ++pt) zz4[pt] = *(const u32x2*)(P0 + row * ABPAD + 1792 + g * 256 + j * 64 + pt * 16 + fq * 4);
; #pragma unroll
;         for (int nt = 0; nt < 8; ++nt) { float mv[4];
; #pragma unroll
;             for (int i = 0; i < 4; ++i) { const int s = nt * 16 + fq * 4 + i;
;                 const float ff = (s <= l) ? __expf(cfl - cf[s]) * df[s] : 0.f; const float fb = (s >= l) ? __expf(cbl - cbw[s]) * db[s] : 0.f;
;                 mv[i] = sc[nt][i] * (ff + fb); }
;             u32x2 o; o.x = pk2(mv[0], mv[1]); o.y = pk2(mv[2], mv[3]); *(LAS u32x2*)(Mw + fr * SLD + nt * 16 + fq * 4) = o; }
.LBB0_844:
	v_readlane_b32 s62, v253, 0
	v_readlane_b32 s63, v253, 1
	s_brev_b32 s60, 28
	s_nop 0
	v_lshl_add_u64 v[32:33], s[62:63], 0, v[134:135]
	v_add_co_u32_e32 v34, vcc, s60, v32
	s_mov_b32 s60, 0x38001000
	s_nop 0
	v_addc_co_u32_e32 v35, vcc, 0, v33, vcc
	v_add_co_u32_e32 v36, vcc, s60, v32
	s_mov_b32 s60, 0x38002000
	s_nop 0
	v_addc_co_u32_e32 v37, vcc, 0, v33, vcc
	v_add_co_u32_e32 v38, vcc, s60, v32
	s_mov_b32 s60, 0x38003000
	s_nop 0
	v_addc_co_u32_e32 v39, vcc, 0, v33, vcc
	v_add_co_u32_e32 v32, vcc, s60, v32
	global_load_dwordx4 v[84:87], v[36:37], off offset:-4096
	global_load_dwordx4 v[80:83], v[36:37], off
	v_addc_co_u32_e32 v33, vcc, 0, v33, vcc
	global_load_dwordx4 v[88:91], v[32:33], off
	global_load_dwordx4 v[64:67], v[32:33], off offset:64
	global_load_dwordx4 v[76:79], v[34:35], off offset:64
	global_load_dwordx4 v[60:63], v[34:35], off offset:128
	global_load_dwordx4 v[72:75], v[36:37], off offset:64
	global_load_dwordx4 v[56:59], v[36:37], off offset:128
	global_load_dwordx4 v[68:71], v[38:39], off offset:64
	global_load_dwordx4 v[44:47], v[34:35], off offset:192
	global_load_dwordx4 v[92:95], v[32:33], off offset:-4096
	global_load_dwordx4 v[40:43], v[36:37], off offset:192
	global_load_dwordx4 v[52:55], v[38:39], off offset:128
	s_nop 0
	global_load_dwordx4 v[36:39], v[38:39], off offset:192
	s_nop 0
	global_load_dwordx4 v[48:51], v[32:33], off offset:128
	s_nop 0
	global_load_dwordx4 v[32:35], v[32:33], off offset:192
	v_lshl_add_u64 v[96:97], s[62:63], 0, v[132:133]
	global_load_dwordx2 v[142:143], v[96:97], off offset:-64
	global_load_dwordx2 v[140:141], v[96:97], off offset:-32
	global_load_dwordx2 v[138:139], v[96:97], off
	global_load_dwordx2 v[136:137], v[96:97], off offset:32
	v_add_u32_e32 v96, 0, v182
	v_add_u32_e32 v97, 0x23000, v96
	v_add_u32_e32 v96, 0x23200, v96
	ds_read_b32 v185, v97
	ds_read_b32 v184, v96
	v_add_u32_e32 v96, 0x22000, v181
	ds_read_b128 v[202:205], v96 offset:4096
	ds_read_b128 v[206:209], v96
	ds_read_b128 v[210:213], v96 offset:4608
	ds_read_b128 v[214:217], v96 offset:512
	ds_read_b128 v[218:221], v96 offset:4160
	ds_read_b128 v[222:225], v96 offset:64
	ds_read_b128 v[226:229], v96 offset:4672
	ds_read_b128 v[230:233], v96 offset:576
	s_waitcnt lgkmcnt(4)
	v_readlane_b32 s60, v253, 48
	v_readlane_b32 s61, v253, 49
	v_readlane_b32 s62, v253, 54
	v_readlane_b32 s63, v253, 55
	v_sub_f32_e32 v202, v185, v202
	v_sub_f32_e32 v210, v184, v210
	v_mul_f32_e32 v202, 0x3fb8aa3b, v202
	v_mul_f32_e32 v210, 0x3fb8aa3b, v210
	v_exp_f32_e32 v202, v202
	v_exp_f32_e32 v210, v210
	v_mul_f32_e32 v202, v206, v202
	v_mul_f32_e32 v210, v214, v210
	v_cndmask_b32_e64 v202, 0, v202, s[60:61]
	v_cndmask_b32_e64 v210, 0, v210, s[62:63]
	v_add_f32_e32 v202, v202, v210
	v_mul_f32_e32 v202, v0, v202
	v_readlane_b32 s60, v253, 52
	v_readlane_b32 s61, v253, 53
	v_readlane_b32 s62, v253, 42
	v_readlane_b32 s63, v253, 43
	v_sub_f32_e32 v203, v185, v203
	v_sub_f32_e32 v211, v184, v211
	v_mul_f32_e32 v203, 0x3fb8aa3b, v203
	v_mul_f32_e32 v211, 0x3fb8aa3b, v211
	v_exp_f32_e32 v203, v203
	v_exp_f32_e32 v211, v211
	v_mul_f32_e32 v203, v207, v203
	v_mul_f32_e32 v211, v215, v211
	v_cndmask_b32_e64 v203, 0, v203, s[60:61]
	v_cndmask_b32_e64 v211, 0, v211, s[62:63]
	v_add_f32_e32 v203, v203, v211
	v_mul_f32_e32 v203, v1, v203
	v_readlane_b32 s60, v253, 46
	v_readlane_b32 s61, v253, 47
	v_readlane_b32 s62, v253, 50
	v_readlane_b32 s63, v253, 51
	v_sub_f32_e32 v204, v185, v204
	v_sub_f32_e32 v212, v184, v212
	v_mul_f32_e32 v204, 0x3fb8aa3b, v204
	v_mul_f32_e32 v212, 0x3fb8aa3b, v212
	v_exp_f32_e32 v204, v204
	v_exp_f32_e32 v212, v212
	v_mul_f32_e32 v204, v208, v204
	v_mul_f32_e32 v212, v216, v212
	v_cndmask_b32_e64 v204, 0, v204, s[60:61]
	v_cndmask_b32_e64 v212, 0, v212, s[62:63]
	v_add_f32_e32 v204, v204, v212
	v_mul_f32_e32 v204, v2, v204
	v_readlane_b32 s60, v253, 44
	v_readlane_b32 s61, v253, 45
	v_readlane_b32 s62, v253, 40
	v_readlane_b32 s63, v253, 41
	v_sub_f32_e32 v205, v185, v205
	v_sub_f32_e32 v213, v184, v213
	v_mul_f32_e32 v205, 0x3fb8aa3b, v205
	v_mul_f32_e32 v213, 0x3fb8aa3b, v213
	v_exp_f32_e32 v205, v205
	v_exp_f32_e32 v213, v213
	v_mul_f32_e32 v205, v209, v205
	v_mul_f32_e32 v213, v217, v213
	v_cndmask_b32_e64 v205, 0, v205, s[60:61]
	v_cndmask_b32_e64 v213, 0, v213, s[62:63]
	v_add_f32_e32 v205, v205, v213
	v_mul_f32_e32 v205, v3, v205
	v_cvt_pk_bf16_f32 v202, v202, v203
	v_cvt_pk_bf16_f32 v203, v204, v205
	ds_write_b64 v170, v[202:203] offset:34816
	ds_read_b128 v[202:205], v96 offset:4224
	ds_read_b128 v[206:209], v96 offset:128
	ds_read_b128 v[210:213], v96 offset:4736
	ds_read_b128 v[214:217], v96 offset:640
	s_waitcnt lgkmcnt(5)
; #define LAS __attribute__((address_space(3)))
; __device__ __forceinline__ unsigned pk2(float lo, float hi) { const f32x2 v = {lo, hi}; return __builtin_bit_cast(unsigned, __builtin_convertvector(v, bf16x2_t)); }
; __device__ __forceinline__ void ssd_s3_unit(LAS unsigned char* lds, int unit, const bf16_t* P0, const float* cw, const float* cb, const float* dt_bias, const float* a_log, const float* dskip, const float* norm_w,
;                                             const bf16_t* STATES, bf16_t* OMIX) {
;     ...
;         for (int nt = 0; nt < 8; ++nt) { float mv[4];
; #pragma unroll
;             for (int i = 0; i < 4; ++i) { const int s = nt * 16 + fq * 4 + i;
;                 const float ff = (s <= l) ? __expf(cfl - cf[s]) * df[s] : 0.f; const float fb = (s >= l) ? __expf(cbl - cbw[s]) * db[s] : 0.f;
;                 mv[i] = sc[nt][i] * (ff + fb); }
;             u32x2 o; o.x = pk2(mv[0], mv[1]); o.y = pk2(mv[2], mv[3]); *(LAS u32x2*)(Mw + fr * SLD + nt * 16 + fq * 4) = o; }
	v_readlane_b32 s60, v253, 38
	v_readlane_b32 s61, v253, 39
	v_readlane_b32 s62, v254, 14
	v_readlane_b32 s63, v254, 15
	v_sub_f32_e32 v218, v185, v218
	v_sub_f32_e32 v226, v184, v226
	v_mul_f32_e32 v218, 0x3fb8aa3b, v218
	v_mul_f32_e32 v226, 0x3fb8aa3b, v226
	v_exp_f32_e32 v218, v218
	v_exp_f32_e32 v226, v226
	v_mul_f32_e32 v218, v222, v218
	v_mul_f32_e32 v226, v230, v226
	v_cndmask_b32_e64 v218, 0, v218, s[60:61]
	v_cndmask_b32_e64 v226, 0, v226, s[62:63]
	v_add_f32_e32 v218, v218, v226
	v_mul_f32_e32 v218, v4, v218
	v_readlane_b32 s60, v254, 16
	v_readlane_b32 s61, v254, 17
	v_readlane_b32 s62, v254, 18
	v_readlane_b32 s63, v254, 19
	v_sub_f32_e32 v219, v185, v219
	v_sub_f32_e32 v227, v184, v227
	v_mul_f32_e32 v219, 0x3fb8aa3b, v219
	v_mul_f32_e32 v227, 0x3fb8aa3b, v227
	v_exp_f32_e32 v219, v219
	v_exp_f32_e32 v227, v227
	v_mul_f32_e32 v219, v223, v219
	v_mul_f32_e32 v227, v231, v227
	v_cndmask_b32_e64 v219, 0, v219, s[60:61]
	v_cndmask_b32_e64 v227, 0, v227, s[62:63]
	v_add_f32_e32 v219, v219, v227
	v_mul_f32_e32 v219, v5, v219
	v_readlane_b32 s60, v254, 20
	v_readlane_b32 s61, v254, 21
	v_readlane_b32 s62, v254, 22
	v_readlane_b32 s63, v254, 23
	v_sub_f32_e32 v220, v185, v220
	v_sub_f32_e32 v228, v184, v228
	v_mul_f32_e32 v220, 0x3fb8aa3b, v220
	v_mul_f32_e32 v228, 0x3fb8aa3b, v228
	v_exp_f32_e32 v220, v220
	v_exp_f32_e32 v228, v228
	v_mul_f32_e32 v220, v224, v220
	v_mul_f32_e32 v228, v232, v228
	v_cndmask_b32_e64 v220, 0, v220, s[60:61]
	v_cndmask_b32_e64 v228, 0, v228, s[62:63]
	v_add_f32_e32 v220, v220, v228
	v_mul_f32_e32 v220, v6, v220
	v_readlane_b32 s60, v254, 24
	v_readlane_b32 s61, v254, 25
	v_readlane_b32 s62, v254, 26
	v_readlane_b32 s63, v254, 27
	v_sub_f32_e32 v221, v185, v221
	v_sub_f32_e32 v229, v184, v229
	v_mul_f32_e32 v221, 0x3fb8aa3b, v221
	v_mul_f32_e32 v229, 0x3fb8aa3b, v229
	v_exp_f32_e32 v221, v221
	v_exp_f32_e32 v229, v229
	v_mul_f32_e32 v221, v225, v221
	v_mul_f32_e32 v229, v233, v229
	v_cndmask_b32_e64 v221, 0, v221, s[60:61]
	v_cndmask_b32_e64 v229, 0, v229, s[62:63]
	v_add_f32_e32 v221, v221, v229
	v_mul_f32_e32 v221, v7, v221
	v_cvt_pk_bf16_f32 v218, v218, v219
	v_cvt_pk_bf16_f32 v219, v220, v221
	ds_write_b64 v170, v[218:219] offset:34848
	ds_read_b128 v[218:221], v96 offset:4288
	ds_read_b128 v[222:225], v96 offset:192
	ds_read_b128 v[226:229], v96 offset:4800
	ds_read_b128 v[230:233], v96 offset:704
	s_waitcnt lgkmcnt(5)
	v_readlane_b32 s60, v254, 28
	v_readlane_b32 s61, v254, 29
	v_readlane_b32 s62, v254, 30
	v_readlane_b32 s63, v254, 31
	v_sub_f32_e32 v202, v185, v202
	v_sub_f32_e32 v210, v184, v210
	v_mul_f32_e32 v202, 0x3fb8aa3b, v202
	v_mul_f32_e32 v210, 0x3fb8aa3b, v210
	v_exp_f32_e32 v202, v202
	v_exp_f32_e32 v210, v210
	v_mul_f32_e32 v202, v206, v202
	v_mul_f32_e32 v210, v214, v210
	v_cndmask_b32_e64 v202, 0, v202, s[60:61]
	v_cndmask_b32_e64 v210, 0, v210, s[62:63]
	v_add_f32_e32 v202, v202, v210
	v_mul_f32_e32 v202, v8, v202
	v_readlane_b32 s60, v254, 32
	v_readlane_b32 s61, v254, 33
	v_readlane_b32 s62, v254, 34
	v_readlane_b32 s63, v254, 35
	v_sub_f32_e32 v203, v185, v203
	v_sub_f32_e32 v211, v184, v211
	v_mul_f32_e32 v203, 0x3fb8aa3b, v203
	v_mul_f32_e32 v211, 0x3fb8aa3b, v211
	v_exp_f32_e32 v203, v203
	v_exp_f32_e32 v211, v211
	v_mul_f32_e32 v203, v207, v203
	v_mul_f32_e32 v211, v215, v211
	v_cndmask_b32_e64 v203, 0, v203, s[60:61]
	v_cndmask_b32_e64 v211, 0, v211, s[62:63]
	v_add_f32_e32 v203, v203, v211
	v_mul_f32_e32 v203, v9, v203
	v_readlane_b32 s60, v254, 36
	v_readlane_b32 s61, v254, 37
	v_readlane_b32 s62, v254, 38
	v_readlane_b32 s63, v254, 39
	v_sub_f32_e32 v204, v185, v204
	v_sub_f32_e32 v212, v184, v212
	v_mul_f32_e32 v204, 0x3fb8aa3b, v204
	v_mul_f32_e32 v212, 0x3fb8aa3b, v212
	v_exp_f32_e32 v204, v204
	v_exp_f32_e32 v212, v212
	v_mul_f32_e32 v204, v208, v204
	v_mul_f32_e32 v212, v216, v212
	v_cndmask_b32_e64 v204, 0, v204, s[60:61]
	v_cndmask_b32_e64 v212, 0, v212, s[62:63]
	v_add_f32_e32 v204, v204, v212
	v_mul_f32_e32 v204, v10, v204
	v_sub_f32_e32 v205, v185, v205
	v_sub_f32_e32 v213, v184, v213
	v_mul_f32_e32 v205, 0x3fb8aa3b, v205
	v_mul_f32_e32 v213, 0x3fb8aa3b, v213
	v_exp_f32_e32 v205, v205
	v_exp_f32_e32 v213, v213
	v_mul_f32_e32 v205, v209, v205
	v_mul_f32_e32 v213, v217, v213
	v_cndmask_b32_e64 v205, 0, v205, s[66:67]
	v_cndmask_b32_e64 v213, 0, v213, s[68:69]
	v_add_f32_e32 v205, v205, v213
	v_mul_f32_e32 v205, v11, v205
	v_cvt_pk_bf16_f32 v202, v202, v203
	v_cvt_pk_bf16_f32 v203, v204, v205
	ds_write_b64 v170, v[202:203] offset:34880
	ds_read_b128 v[202:205], v96 offset:4352
	ds_read_b128 v[206:209], v96 offset:256
	ds_read_b128 v[210:213], v96 offset:4864
	ds_read_b128 v[214:217], v96 offset:768
	s_waitcnt lgkmcnt(5)
; #define LAS __attribute__((address_space(3)))
; __device__ __forceinline__ unsigned pk2(float lo, float hi) { const f32x2 v = {lo, hi}; return __builtin_bit_cast(unsigned, __builtin_convertvector(v, bf16x2_t)); }
; __device__ __forceinline__ void ssd_s3_unit(LAS unsigned char* lds, int unit, const bf16_t* P0, const float* cw, const float* cb, const float* dt_bias, const float* a_log, const float* dskip, const float* norm_w,
;                                             const bf16_t* STATES, bf16_t* OMIX) {
;     ...
;         for (int nt = 0; nt < 8; ++nt) { float mv[4];
; #pragma unroll
;             for (int i = 0; i < 4; ++i) { const int s = nt * 16 + fq * 4 + i;
;                 const float ff = (s <= l) ? __expf(cfl - cf[s]) * df[s] : 0.f; const float fb = (s >= l) ? __expf(cbl - cbw[s]) * db[s] : 0.f;
;                 mv[i] = sc[nt][i] * (ff + fb); }
;             u32x2 o; o.x = pk2(mv[0], mv[1]); o.y = pk2(mv[2], mv[3]); *(LAS u32x2*)(Mw + fr * SLD + nt * 16 + fq * 4) = o; }
	v_sub_f32_e32 v218, v185, v218
	v_sub_f32_e32 v226, v184, v226
	v_mul_f32_e32 v218, 0x3fb8aa3b, v218
	v_mul_f32_e32 v226, 0x3fb8aa3b, v226
	v_exp_f32_e32 v218, v218
	v_exp_f32_e32 v226, v226
	v_mul_f32_e32 v218, v222, v218
	v_mul_f32_e32 v226, v230, v226
	v_cndmask_b32_e64 v218, 0, v218, s[70:71]
	v_cndmask_b32_e64 v226, 0, v226, s[72:73]
	v_add_f32_e32 v218, v218, v226
	v_mul_f32_e32 v218, v12, v218
	v_sub_f32_e32 v219, v185, v219
	v_sub_f32_e32 v227, v184, v227
	v_mul_f32_e32 v219, 0x3fb8aa3b, v219
	v_mul_f32_e32 v227, 0x3fb8aa3b, v227
	v_exp_f32_e32 v219, v219
	v_exp_f32_e32 v227, v227
	v_mul_f32_e32 v219, v223, v219
	v_mul_f32_e32 v227, v231, v227
	v_cndmask_b32_e64 v219, 0, v219, s[74:75]
	v_cndmask_b32_e64 v227, 0, v227, s[76:77]
	v_add_f32_e32 v219, v219, v227
	v_mul_f32_e32 v219, v13, v219
	v_sub_f32_e32 v220, v185, v220
	v_sub_f32_e32 v228, v184, v228
	v_mul_f32_e32 v220, 0x3fb8aa3b, v220
	v_mul_f32_e32 v228, 0x3fb8aa3b, v228
	v_exp_f32_e32 v220, v220
	v_exp_f32_e32 v228, v228
	v_mul_f32_e32 v220, v224, v220
	v_mul_f32_e32 v228, v232, v228
	v_cndmask_b32_e64 v220, 0, v220, s[78:79]
	v_cndmask_b32_e64 v228, 0, v228, s[80:81]
	v_add_f32_e32 v220, v220, v228
	v_mul_f32_e32 v220, v14, v220
	v_sub_f32_e32 v221, v185, v221
	v_sub_f32_e32 v229, v184, v229
	v_mul_f32_e32 v221, 0x3fb8aa3b, v221
	v_mul_f32_e32 v229, 0x3fb8aa3b, v229
	v_exp_f32_e32 v221, v221
	v_exp_f32_e32 v229, v229
	v_mul_f32_e32 v221, v225, v221
	v_mul_f32_e32 v229, v233, v229
	v_cndmask_b32_e64 v221, 0, v221, s[82:83]
	v_cndmask_b32_e64 v229, 0, v229, s[84:85]
	v_add_f32_e32 v221, v221, v229
	v_mul_f32_e32 v221, v15, v221
	v_cvt_pk_bf16_f32 v218, v218, v219
	v_cvt_pk_bf16_f32 v219, v220, v221
	ds_write_b64 v170, v[218:219] offset:34912
	ds_read_b128 v[218:221], v96 offset:4416
	ds_read_b128 v[222:225], v96 offset:320
	ds_read_b128 v[226:229], v96 offset:4928
	ds_read_b128 v[230:233], v96 offset:832
	s_waitcnt lgkmcnt(5)
	v_sub_f32_e32 v202, v185, v202
	v_sub_f32_e32 v210, v184, v210
	v_mul_f32_e32 v202, 0x3fb8aa3b, v202
	v_mul_f32_e32 v210, 0x3fb8aa3b, v210
	v_exp_f32_e32 v202, v202
	v_exp_f32_e32 v210, v210
	v_mul_f32_e32 v202, v206, v202
	v_mul_f32_e32 v210, v214, v210
	v_cndmask_b32_e64 v202, 0, v202, s[86:87]
	v_cndmask_b32_e64 v210, 0, v210, s[88:89]
	v_add_f32_e32 v202, v202, v210
	v_mul_f32_e32 v202, v16, v202
	v_sub_f32_e32 v203, v185, v203
	v_sub_f32_e32 v211, v184, v211
	v_mul_f32_e32 v203, 0x3fb8aa3b, v203
	v_mul_f32_e32 v211, 0x3fb8aa3b, v211
	v_exp_f32_e32 v203, v203
	v_exp_f32_e32 v211, v211
	v_mul_f32_e32 v203, v207, v203
	v_mul_f32_e32 v211, v215, v211
	v_cndmask_b32_e64 v203, 0, v203, s[90:91]
	v_cndmask_b32_e64 v211, 0, v211, s[92:93]
	v_add_f32_e32 v203, v203, v211
	v_mul_f32_e32 v203, v17, v203
	v_sub_f32_e32 v204, v185, v204
	v_sub_f32_e32 v212, v184, v212
	v_mul_f32_e32 v204, 0x3fb8aa3b, v204
	v_mul_f32_e32 v212, 0x3fb8aa3b, v212
	v_exp_f32_e32 v204, v204
	v_exp_f32_e32 v212, v212
	v_mul_f32_e32 v204, v208, v204
	v_mul_f32_e32 v212, v216, v212
	v_cndmask_b32_e64 v204, 0, v204, s[94:95]
	v_cndmask_b32_e64 v212, 0, v212, s[96:97]
	v_add_f32_e32 v204, v204, v212
	v_mul_f32_e32 v204, v18, v204
	v_sub_f32_e32 v205, v185, v205
	v_sub_f32_e32 v213, v184, v213
	v_mul_f32_e32 v205, 0x3fb8aa3b, v205
	v_mul_f32_e32 v213, 0x3fb8aa3b, v213
	v_exp_f32_e32 v205, v205
	v_exp_f32_e32 v213, v213
	v_mul_f32_e32 v205, v209, v205
	v_mul_f32_e32 v213, v217, v213
	v_cndmask_b32_e64 v205, 0, v205, s[4:5]
	v_cndmask_b32_e64 v213, 0, v213, s[8:9]
	v_add_f32_e32 v205, v205, v213
	v_mul_f32_e32 v205, v19, v205
	v_cvt_pk_bf16_f32 v202, v202, v203
	v_cvt_pk_bf16_f32 v203, v204, v205
	ds_write_b64 v170, v[202:203] offset:34944
	ds_read_b128 v[202:205], v96 offset:4480
	ds_read_b128 v[206:209], v96 offset:384
	ds_read_b128 v[210:213], v96 offset:4992
	ds_read_b128 v[214:217], v96 offset:896
	s_waitcnt lgkmcnt(5)
; #define LAS __attribute__((address_space(3)))
; __device__ __forceinline__ unsigned pk2(float lo, float hi) { const f32x2 v = {lo, hi}; return __builtin_bit_cast(unsigned, __builtin_convertvector(v, bf16x2_t)); }
; __device__ __forceinline__ void ssd_s3_unit(LAS unsigned char* lds, int unit, const bf16_t* P0, const float* cw, const float* cb, const float* dt_bias, const float* a_log, const float* dskip, const float* norm_w,
;                                             const bf16_t* STATES, bf16_t* OMIX) {
;     ...
;         for (int nt = 0; nt < 8; ++nt) { float mv[4];
; #pragma unroll
;             for (int i = 0; i < 4; ++i) { const int s = nt * 16 + fq * 4 + i;
;                 const float ff = (s <= l) ? __expf(cfl - cf[s]) * df[s] : 0.f; const float fb = (s >= l) ? __expf(cbl - cbw[s]) * db[s] : 0.f;
;                 mv[i] = sc[nt][i] * (ff + fb); }
;             u32x2 o; o.x = pk2(mv[0], mv[1]); o.y = pk2(mv[2], mv[3]); *(LAS u32x2*)(Mw + fr * SLD + nt * 16 + fq * 4) = o; }
	v_sub_f32_e32 v218, v185, v218
	v_sub_f32_e32 v226, v184, v226
	v_mul_f32_e32 v218, 0x3fb8aa3b, v218
	v_mul_f32_e32 v226, 0x3fb8aa3b, v226
	v_exp_f32_e32 v218, v218
	v_exp_f32_e32 v226, v226
	v_mul_f32_e32 v218, v222, v218
	v_mul_f32_e32 v226, v230, v226
	v_cndmask_b32_e64 v218, 0, v218, s[10:11]
	v_cndmask_b32_e64 v226, 0, v226, s[12:13]
	v_add_f32_e32 v218, v218, v226
	v_mul_f32_e32 v218, v20, v218
	v_sub_f32_e32 v219, v185, v219
	v_sub_f32_e32 v227, v184, v227
	v_mul_f32_e32 v219, 0x3fb8aa3b, v219
	v_mul_f32_e32 v227, 0x3fb8aa3b, v227
	v_exp_f32_e32 v219, v219
	v_exp_f32_e32 v227, v227
	v_mul_f32_e32 v219, v223, v219
	v_mul_f32_e32 v227, v231, v227
	v_cndmask_b32_e64 v219, 0, v219, s[14:15]
	v_cndmask_b32_e64 v227, 0, v227, s[16:17]
	v_add_f32_e32 v219, v219, v227
	v_mul_f32_e32 v219, v21, v219
	v_sub_f32_e32 v220, v185, v220
	v_sub_f32_e32 v228, v184, v228
	v_mul_f32_e32 v220, 0x3fb8aa3b, v220
	v_mul_f32_e32 v228, 0x3fb8aa3b, v228
	v_exp_f32_e32 v220, v220
	v_exp_f32_e32 v228, v228
	v_mul_f32_e32 v220, v224, v220
	v_mul_f32_e32 v228, v232, v228
	v_cndmask_b32_e64 v220, 0, v220, s[6:7]
	v_cndmask_b32_e64 v228, 0, v228, s[18:19]
	v_add_f32_e32 v220, v220, v228
	v_mul_f32_e32 v220, v22, v220
	v_sub_f32_e32 v221, v185, v221
	v_sub_f32_e32 v229, v184, v229
	v_mul_f32_e32 v221, 0x3fb8aa3b, v221
	v_mul_f32_e32 v229, 0x3fb8aa3b, v229
	v_exp_f32_e32 v221, v221
	v_exp_f32_e32 v229, v229
	v_mul_f32_e32 v221, v225, v221
	v_mul_f32_e32 v229, v233, v229
	v_cndmask_b32_e64 v221, 0, v221, s[20:21]
	v_cndmask_b32_e64 v229, 0, v229, s[2:3]
	v_add_f32_e32 v221, v221, v229
	v_mul_f32_e32 v221, v23, v221
	v_cvt_pk_bf16_f32 v218, v218, v219
	v_cvt_pk_bf16_f32 v219, v220, v221
	ds_write_b64 v170, v[218:219] offset:34976
	ds_read_b128 v[218:221], v96 offset:4544
	ds_read_b128 v[222:225], v96 offset:448
	ds_read_b128 v[226:229], v96 offset:5056
	ds_read_b128 v[230:233], v96 offset:960
	s_waitcnt lgkmcnt(5)
	v_sub_f32_e32 v202, v185, v202
	v_sub_f32_e32 v210, v184, v210
	v_mul_f32_e32 v202, 0x3fb8aa3b, v202
	v_mul_f32_e32 v210, 0x3fb8aa3b, v210
	v_exp_f32_e32 v202, v202
	v_exp_f32_e32 v210, v210
	v_mul_f32_e32 v202, v206, v202
	v_mul_f32_e32 v210, v214, v210
	v_cndmask_b32_e64 v202, 0, v202, s[0:1]
	v_cndmask_b32_e64 v210, 0, v210, s[22:23]
	v_add_f32_e32 v202, v202, v210
	v_mul_f32_e32 v202, v24, v202
	v_sub_f32_e32 v203, v185, v203
	v_sub_f32_e32 v211, v184, v211
	v_mul_f32_e32 v203, 0x3fb8aa3b, v203
	v_mul_f32_e32 v211, 0x3fb8aa3b, v211
	v_exp_f32_e32 v203, v203
	v_exp_f32_e32 v211, v211
	v_mul_f32_e32 v203, v207, v203
	v_mul_f32_e32 v211, v215, v211
	v_cndmask_b32_e64 v203, 0, v203, s[24:25]
	v_cndmask_b32_e64 v211, 0, v211, s[26:27]
	v_add_f32_e32 v203, v203, v211
	v_mul_f32_e32 v203, v25, v203
	v_sub_f32_e32 v204, v185, v204
	v_sub_f32_e32 v212, v184, v212
	v_mul_f32_e32 v204, 0x3fb8aa3b, v204
	v_mul_f32_e32 v212, 0x3fb8aa3b, v212
	v_exp_f32_e32 v204, v204
	v_exp_f32_e32 v212, v212
	v_mul_f32_e32 v204, v208, v204
	v_mul_f32_e32 v212, v216, v212
	v_cndmask_b32_e64 v204, 0, v204, s[28:29]
	v_cndmask_b32_e64 v212, 0, v212, s[30:31]
	v_add_f32_e32 v204, v204, v212
	v_mul_f32_e32 v204, v26, v204
	v_sub_f32_e32 v205, v185, v205
	v_sub_f32_e32 v213, v184, v213
	v_mul_f32_e32 v205, 0x3fb8aa3b, v205
	v_mul_f32_e32 v213, 0x3fb8aa3b, v213
	v_exp_f32_e32 v205, v205
	v_exp_f32_e32 v213, v213
	v_mul_f32_e32 v205, v209, v205
	v_mul_f32_e32 v213, v217, v213
	v_cndmask_b32_e64 v205, 0, v205, s[34:35]
	v_cndmask_b32_e64 v213, 0, v213, s[36:37]
	v_add_f32_e32 v205, v205, v213
	v_mul_f32_e32 v205, v27, v205
	v_cvt_pk_bf16_f32 v202, v202, v203
	v_cvt_pk_bf16_f32 v203, v204, v205
	ds_write_b64 v170, v[202:203] offset:35008
	s_waitcnt lgkmcnt(1)
	v_sub_f32_e32 v218, v185, v218
	v_sub_f32_e32 v226, v184, v226
	v_mul_f32_e32 v218, 0x3fb8aa3b, v218
	v_mul_f32_e32 v226, 0x3fb8aa3b, v226
	v_exp_f32_e32 v218, v218
	v_exp_f32_e32 v226, v226
	v_mul_f32_e32 v218, v222, v218
	v_mul_f32_e32 v226, v230, v226
	v_cndmask_b32_e64 v218, 0, v218, s[38:39]
	v_cndmask_b32_e64 v226, 0, v226, s[40:41]
	v_add_f32_e32 v218, v218, v226
	v_mul_f32_e32 v218, v28, v218
	v_sub_f32_e32 v219, v185, v219
	v_sub_f32_e32 v227, v184, v227
	v_mul_f32_e32 v219, 0x3fb8aa3b, v219
	v_mul_f32_e32 v227, 0x3fb8aa3b, v227
	v_exp_f32_e32 v219, v219
	v_exp_f32_e32 v227, v227
	v_mul_f32_e32 v219, v223, v219
	v_mul_f32_e32 v227, v231, v227
	v_cndmask_b32_e64 v219, 0, v219, s[42:43]
	v_cndmask_b32_e64 v227, 0, v227, s[44:45]
	v_add_f32_e32 v219, v219, v227
	v_mul_f32_e32 v219, v29, v219
	v_sub_f32_e32 v220, v185, v220
	v_sub_f32_e32 v228, v184, v228
	v_mul_f32_e32 v220, 0x3fb8aa3b, v220
	v_mul_f32_e32 v228, 0x3fb8aa3b, v228
	v_exp_f32_e32 v220, v220
	v_exp_f32_e32 v228, v228
	v_mul_f32_e32 v220, v224, v220
	v_mul_f32_e32 v228, v232, v228
	v_cndmask_b32_e64 v220, 0, v220, s[46:47]
	v_cndmask_b32_e64 v228, 0, v228, s[48:49]
	v_add_f32_e32 v220, v220, v228
	v_mul_f32_e32 v220, v30, v220
	v_sub_f32_e32 v221, v185, v221
	v_sub_f32_e32 v229, v184, v229
	v_mul_f32_e32 v221, 0x3fb8aa3b, v221
	v_mul_f32_e32 v229, 0x3fb8aa3b, v229
	v_exp_f32_e32 v221, v221
	v_exp_f32_e32 v229, v229
	v_mul_f32_e32 v221, v225, v221
	v_mul_f32_e32 v229, v233, v229
	v_cndmask_b32_e64 v221, 0, v221, s[50:51]
	v_cndmask_b32_e64 v229, 0, v229, s[52:53]
	v_add_f32_e32 v221, v221, v229
	v_mul_f32_e32 v221, v31, v221
	v_cvt_pk_bf16_f32 v218, v218, v219
	v_cvt_pk_bf16_f32 v219, v220, v221
	ds_write_b64 v170, v[218:219] offset:35040
	s_branch .LBB0_843
